# conv weights + ssq staged at unit start into double-buffered LDS (static 16KiB above the 144KiB dynamic), no vm wait at epilogue start
# baseline (speedup 1.0000x reference)
; template <class Epi, class Sched, bool ALIGN_EPI = false, bool SP2 = false, bool F8 = false>
; __device__ __forceinline__ void gemm_phase(PG8_LAS unsigned char* lds, const Gemm g, const Sched& S, const Epi& E) {
;     ...
;     Unit cur, nxt; int ui = 0;
;     if (!S.next(0, cur)) return;
;     f32x4 acc[2][2][4][2];
; #pragma unroll
;     for (int a = 0; a < 2; ++a)
; #pragma unroll
;         for (int b = 0; b < 2; ++b)
; #pragma unroll
;             for (int m = 0; m < 4; ++m)
; #pragma unroll
;                 for (int n = 0; n < 2; ++n) acc[a][b][m][n] = (f32x4){0.f, 0.f, 0.f, 0.f};
;     bf16x8 At[4][2], B0[2][2], B1[2][2];
;     const char* cA = (const char*)g.A + (size_t)cur.pm * tA + (size_t)(cur.pn >> g.gshift) * g.goff; const char* cB = (const char*)g.Bt + (size_t)cur.pn * tB;
;     S.a_ready(cur);
.LBB0_769:
	s_and_b32 s98, s29, 1
	s_lshl_b32 s101, s98, 12
	s_add_i32 s101, s101, 0x24000
	s_lshr_b32 s98, s7, 10
	s_cmp_gt_u32 s98, 3
	s_cbranch_scc1 .Lhdr_skip
	s_mov_b32 s99, 0
	s_mov_b32 s100, 0x15800
	s_cmp_eq_u32 s98, 1
	s_cselect_b32 s99, 0x2b000, s99
	s_cselect_b32 s100, 0xac00, s100
	s_cmp_eq_u32 s98, 2
	s_cselect_b32 s99, 0x20400, s99
	s_cselect_b32 s100, 0x35c00, s100
	s_cmp_eq_u32 s98, 3
	s_cselect_b32 s99, 0, s99
	s_cselect_b32 s100, 0xac00, s100
	v_lshl_add_u32 v248, v239, 4, v238
	v_cmp_lt_u32_e32 vcc, 31, v248
	v_mov_b32_e32 v249, s99
	v_mov_b32_e32 v250, s100
	v_cndmask_b32_e32 v249, v249, v250, vcc
	v_and_b32_e32 v250, 31, v248
	v_lshlrev_b32_e32 v250, 4, v250
	s_lshl_b32 s99, s10, 9
	v_add3_u32 v249, v250, v249, s99
	s_cmp_eq_u32 s98, 3
	s_cselect_b32 vcc_lo, s22, s20
	s_cselect_b32 vcc_hi, s23, s21
	s_lshl_b32 s100, s98, 10
	s_add_i32 m0, s100, s101
	s_nop 0
	global_load_lds_dwordx4 v249, vcc
	s_cmp_lg_u32 s98, 0
	s_cbranch_scc1 .Lhdr_skip
	v_lshlrev_b32_e32 v248, 4, v248
	s_lshl_b32 s99, s76, 10
	v_add_u32_e32 v248, s99, v248
	s_and_b32 s99, s29, 1
	s_lshl_b32 s99, s99, 10
	s_add_i32 m0, s99, 0x26000
	s_mov_b32 vcc_lo, s35
	s_mov_b32 vcc_hi, s96
	global_load_lds_dwordx4 v248, vcc
.Lhdr_skip:
	s_and_b32 s100, s29, 1
	s_lshl_b32 s100, s100, 10
	s_add_i32 s100, s100, 0x26000
	s_ashr_i32 s63, s62, 31
	s_lshl_b64 s[16:17], s[62:63], 21
	s_add_u32 s64, s85, s16
	s_addc_u32 s65, s87, s17
	s_and_b64 s[16:17], s[8:9], exec
	s_cselect_b32 s11, s65, s15
	s_cselect_b32 s63, s64, s14
	s_ashr_i32 s61, s60, 31
	s_lshl_b64 s[16:17], s[60:61], 21
	s_add_u32 s66, s88, s16
	s_addc_u32 s67, s89, s17
	s_and_b64 s[16:17], s[8:9], exec
	s_cselect_b32 s61, s67, s13
	s_cselect_b32 s77, s66, s12
	s_add_u32 s78, s12, 0x100
	s_addc_u32 s79, s13, 0
	s_add_u32 s12, s14, 0x100080
	v_mov_b32_e32 v66, 0
	s_addc_u32 s13, s15, 0
	s_mov_b32 s80, -2
	v_mov_b32_e32 v67, v66
	v_mov_b32_e32 v68, v66
	v_mov_b32_e32 v69, v66
	v_mov_b32_e32 v58, v66
	v_mov_b32_e32 v59, v66
	v_mov_b32_e32 v60, v66
	v_mov_b32_e32 v61, v66
	v_mov_b32_e32 v22, v66
	v_mov_b32_e32 v23, v66
	v_mov_b32_e32 v24, v66
	v_mov_b32_e32 v25, v66
	v_mov_b32_e32 v18, v66
	v_mov_b32_e32 v19, v66
	v_mov_b32_e32 v20, v66
	v_mov_b32_e32 v21, v66
	v_mov_b32_e32 v54, v66
	v_mov_b32_e32 v55, v66
	v_mov_b32_e32 v56, v66
	v_mov_b32_e32 v57, v66
	v_mov_b32_e32 v2, v66
	v_mov_b32_e32 v3, v66
	v_mov_b32_e32 v4, v66
	v_mov_b32_e32 v5, v66
	v_mov_b32_e32 v26, v66
	v_mov_b32_e32 v27, v66
	v_mov_b32_e32 v28, v66
	v_mov_b32_e32 v29, v66
	v_mov_b32_e32 v6, v66
	v_mov_b32_e32 v7, v66
	v_mov_b32_e32 v8, v66
	v_mov_b32_e32 v9, v66
	v_mov_b32_e32 v30, v66
	v_mov_b32_e32 v31, v66
	v_mov_b32_e32 v32, v66
	v_mov_b32_e32 v33, v66
	v_mov_b32_e32 v46, v66
	v_mov_b32_e32 v47, v66
	v_mov_b32_e32 v48, v66
	v_mov_b32_e32 v49, v66
	v_mov_b32_e32 v114, v66
	v_mov_b32_e32 v115, v66
	v_mov_b32_e32 v116, v66
	v_mov_b32_e32 v117, v66
	v_mov_b32_e32 v50, v66
	v_mov_b32_e32 v51, v66
	v_mov_b32_e32 v52, v66
	v_mov_b32_e32 v53, v66
	v_mov_b32_e32 v10, v66
	v_mov_b32_e32 v11, v66
	v_mov_b32_e32 v12, v66
	v_mov_b32_e32 v13, v66
	v_mov_b32_e32 v34, v66
	v_mov_b32_e32 v35, v66
	v_mov_b32_e32 v36, v66
	v_mov_b32_e32 v37, v66
	v_mov_b32_e32 v14, v66
	v_mov_b32_e32 v15, v66
	v_mov_b32_e32 v16, v66
	v_mov_b32_e32 v17, v66
	v_mov_b32_e32 v42, v66
	v_mov_b32_e32 v43, v66
	v_mov_b32_e32 v44, v66
	v_mov_b32_e32 v45, v66
	v_mov_b32_e32 v38, v66
	v_mov_b32_e32 v39, v66
	v_mov_b32_e32 v40, v66
	v_mov_b32_e32 v41, v66
	v_mov_b32_e32 v62, v66
	v_mov_b32_e32 v63, v66
	v_mov_b32_e32 v64, v66
	v_mov_b32_e32 v65, v66
	v_mov_b32_e32 v70, v66
	v_mov_b32_e32 v71, v66
	v_mov_b32_e32 v72, v66
	v_mov_b32_e32 v73, v66
	v_mov_b32_e32 v74, v66
	v_mov_b32_e32 v75, v66
	v_mov_b32_e32 v76, v66
	v_mov_b32_e32 v77, v66
	v_mov_b32_e32 v98, v66
	v_mov_b32_e32 v99, v66
	v_mov_b32_e32 v100, v66
	v_mov_b32_e32 v101, v66
	v_mov_b32_e32 v78, v66
	v_mov_b32_e32 v79, v66
	v_mov_b32_e32 v80, v66
	v_mov_b32_e32 v81, v66
	v_mov_b32_e32 v102, v66
	v_mov_b32_e32 v103, v66
	v_mov_b32_e32 v104, v66
	v_mov_b32_e32 v105, v66
	v_mov_b32_e32 v94, v66
	v_mov_b32_e32 v95, v66
	v_mov_b32_e32 v96, v66
	v_mov_b32_e32 v97, v66
	v_mov_b32_e32 v122, v66
	v_mov_b32_e32 v123, v66
	v_mov_b32_e32 v124, v66
	v_mov_b32_e32 v125, v66
	v_mov_b32_e32 v118, v66
	v_mov_b32_e32 v119, v66
	v_mov_b32_e32 v120, v66
	v_mov_b32_e32 v121, v66
	v_mov_b32_e32 v82, v66
	v_mov_b32_e32 v83, v66
	v_mov_b32_e32 v84, v66
	v_mov_b32_e32 v85, v66
	v_mov_b32_e32 v106, v66
	v_mov_b32_e32 v107, v66
	v_mov_b32_e32 v108, v66
	v_mov_b32_e32 v109, v66
	v_mov_b32_e32 v86, v66
	v_mov_b32_e32 v87, v66
	v_mov_b32_e32 v88, v66
	v_mov_b32_e32 v89, v66
	v_mov_b32_e32 v110, v66
	v_mov_b32_e32 v111, v66
	v_mov_b32_e32 v112, v66
	v_mov_b32_e32 v113, v66
	v_mov_b32_e32 v90, v66
	v_mov_b32_e32 v91, v66
	v_mov_b32_e32 v92, v66
	v_mov_b32_e32 v93, v66
	v_mov_b32_e32 v126, v66
	v_mov_b32_e32 v127, v66
	v_mov_b32_e32 v128, v66
	v_mov_b32_e32 v129, v66

; #define PG8_LAS __attribute__((address_space(3)))
;     __device__ __forceinline__ void run(f32x4 (&acc)[2][2][4][2], const Unit& un, int wr, int wc, int fr, int fq, PG8_LAS unsigned char* xl) const {
;     ...
;         const int cl = wc * 32 + 8 * fq;
; #pragma unroll
;         for (int ai = 0; ai < 2; ++ai)
; #pragma unroll
;             for (int m = 0; m < 4; ++m) { const float iv = __builtin_amdgcn_rsqf(ssq[(size_t)un.pm * BM + wr * 64 + fr + ai * HALF + m * 16] * inv_n + eps);
; #pragma unroll
;                 for (int bj = 0; bj < 2; ++bj)
; #pragma unroll
;                     for (int n = 0; n < 2; ++n) acc[ai][bj][m][n] = acc[ai][bj][m][n] * iv; }
;         PG8_LAS float* X = (PG8_LAS float*)xl;
; #pragma unroll
;         for (int ai = 0; ai < 2; ++ai) { const int blk = ai * 2 + wr;
;             if (fr == 0) {
; #pragma unroll
;                 for (int bj = 0; bj < 2; ++bj) { *(PG8_LAS f32x4*)(X + (blk * 2 + 0) * 256 + bj * 128 + cl) = acc[ai][bj][0][0]; *(PG8_LAS f32x4*)(X + (blk * 2 + 0) * 256 + bj * 128 + cl + 4) = acc[ai][bj][0][1]; } }
;             if (fr == 15) {
; #pragma unroll
;                 for (int bj = 0; bj < 2; ++bj) { *(PG8_LAS f32x4*)(X + (blk * 2 + 1) * 256 + bj * 128 + cl) = acc[ai][bj][3][0]; *(PG8_LAS f32x4*)(X + (blk * 2 + 1) * 256 + bj * 128 + cl + 4) = acc[ai][bj][3][1]; } } }
.LBB0_773:
	s_ashr_i32 s77, s76, 31
	s_lshl_b64 s[12:13], s[76:77], 10
	v_mov_b32_e32 v210, v238
	v_mov_b32_e32 v131, v239
	s_add_u32 s12, s35, s12
	s_addc_u32 s13, s96, s13
	v_ashrrev_i32_e32 v211, 31, v210
	s_lshl_b32 s99, s34, 2
	s_add_i32 s99, s99, s100
	v_lshl_add_u32 v132, v210, 2, s99
	ds_read_b32 v134, v132 offset:192
	ds_read_b32 v130, v132
	ds_read_b32 v214, v132 offset:64
	ds_read_b32 v149, v132 offset:512
	ds_read_b32 v245, v132 offset:576
	ds_read_b32 v211, v132 offset:640
	ds_read_b32 v147, v132 offset:704
	ds_read_b32 v216, v132 offset:128
	v_lshl_add_u32 v196, v131, 3, s70
	v_mov_b32_e32 v247, s101
	v_lshl_add_u32 v247, v196, 2, v247
	v_cmp_lt_i32_e32 vcc, 14, v210
	s_mov_b64 s[12:13], 0
	s_waitcnt lgkmcnt(0)
	v_fmamk_f32 v132, v134, 0x39800000, v244
	v_rsq_f32_e32 v134, v132
	s_nop 0
	v_pk_mul_f32 v[120:121], v[120:121], v[134:135] op_sel_hi:[1,0]
	v_pk_mul_f32 v[118:119], v[118:119], v[134:135] op_sel_hi:[1,0]
	s_and_saveexec_b64 s[14:15], vcc
	s_xor_b64 s[14:15], exec, s[14:15]
	s_cbranch_execz .LBB0_777
	v_cmp_eq_u32_e32 vcc, 15, v210
	s_and_saveexec_b64 s[16:17], vcc
	v_lshl_add_u32 v131, v196, 2, s82
	s_mov_b64 s[12:13], exec
	v_add_u32_e32 v146, 0x400, v131
	ds_write_b128 v131, v[118:121] offset:1024
	s_or_b64 exec, exec, s[16:17]
	s_and_b64 s[12:13], s[12:13], exec

; __global__ void __launch_bounds__(NWAVES * 64, 2) fwd_kernel(Args args) {
;     extern __shared__ __attribute__((aligned(16))) unsigned char lds[];
	.amdhsa_kernel _Z10fwd_kernel4Args
		.amdhsa_group_segment_fixed_size 16384
		.amdhsa_private_segment_fixed_size 0
		.amdhsa_kernarg_size 400
		.amdhsa_user_sgpr_count 2
		.amdhsa_user_sgpr_dispatch_ptr 0
		.amdhsa_user_sgpr_queue_ptr 0
		.amdhsa_user_sgpr_kernarg_segment_ptr 1
		.amdhsa_user_sgpr_dispatch_id 0
		.amdhsa_user_sgpr_kernarg_preload_length 0
		.amdhsa_user_sgpr_kernarg_preload_offset 0
		.amdhsa_user_sgpr_private_segment_size 0
		.amdhsa_uses_dynamic_stack 0
		.amdhsa_enable_private_segment 0
		.amdhsa_system_sgpr_workgroup_id_x 1
		.amdhsa_system_sgpr_workgroup_id_y 0
		.amdhsa_system_sgpr_workgroup_id_z 0
		.amdhsa_system_sgpr_workgroup_info 0
		.amdhsa_system_vgpr_workitem_id 0
		.amdhsa_next_free_vgpr 256
		.amdhsa_next_free_sgpr 102
		.amdhsa_accum_offset 256
		.amdhsa_reserve_vcc 1
		.amdhsa_float_round_mode_32 0
		.amdhsa_float_round_mode_16_64 0
		.amdhsa_float_denorm_mode_32 3
		.amdhsa_float_denorm_mode_16_64 3
		.amdhsa_dx10_clamp 1
		.amdhsa_ieee_mode 1
		.amdhsa_fp16_overflow 0
		.amdhsa_tg_split 0
		.amdhsa_exception_fp_ieee_invalid_op 0
		.amdhsa_exception_fp_denorm_src 0
		.amdhsa_exception_fp_ieee_div_zero 0
		.amdhsa_exception_fp_ieee_overflow 0
		.amdhsa_exception_fp_ieee_underflow 0
		.amdhsa_exception_fp_ieee_inexact 0
		.amdhsa_exception_int_div_zero 0
	.end_amdhsa_kernel

; __global__ void __launch_bounds__(NWAVES * 64, 2) fwd_kernel(Args args) {
;     extern __shared__ __attribute__((aligned(16))) unsigned char lds[];
amdhsa.kernels:
  - .agpr_count:     0
    .args:
      - .offset:         0
        .size:           144
        .value_kind:     by_value
      - .offset:         144
        .size:           4
        .value_kind:     hidden_block_count_x
      - .offset:         148
        .size:           4
        .value_kind:     hidden_block_count_y
      - .offset:         152
        .size:           4
        .value_kind:     hidden_block_count_z
      - .offset:         156
        .size:           2
        .value_kind:     hidden_group_size_x
      - .offset:         158
        .size:           2
        .value_kind:     hidden_group_size_y
      - .offset:         160
        .size:           2
        .value_kind:     hidden_group_size_z
      - .offset:         162
        .size:           2
        .value_kind:     hidden_remainder_x
      - .offset:         164
        .size:           2
        .value_kind:     hidden_remainder_y
      - .offset:         166
        .size:           2
        .value_kind:     hidden_remainder_z
      - .offset:         184
        .size:           8
        .value_kind:     hidden_global_offset_x
      - .offset:         192
        .size:           8
        .value_kind:     hidden_global_offset_y
      - .offset:         200
        .size:           8
        .value_kind:     hidden_global_offset_z
      - .offset:         208
        .size:           2
        .value_kind:     hidden_grid_dims
      - .offset:         264
        .size:           4
        .value_kind:     hidden_dynamic_lds_size
    .group_segment_fixed_size: 16384
    .kernarg_segment_align: 8
    .kernarg_segment_size: 400
    .language:       OpenCL C
    .language_version:
      - 2
      - 0
    .max_flat_workgroup_size: 512
    .name:           _Z10fwd_kernel4Args
    .private_segment_fixed_size: 0
    .sgpr_count:     108
    .sgpr_spill_count: 53
    .symbol:         _Z10fwd_kernel4Args.kd
    .uniform_work_group_size: 1
    .uses_dynamic_stack: false
    .vgpr_count:     256
    .vgpr_spill_count: 0
    .wavefront_size: 64
